# compaction loop v2: SGPR running write addresses, LDS prefetch of next iteration (on top of hand-written fine phase)
# baseline (speedup 1.0000x reference)
.LBB0_441:
	s_or_b64 exec, exec, s[38:39]
	s_xor_b64 s[36:37], s[42:43], -1
	v_mov_b32_e32 v2, 0
	s_barrier
	s_and_saveexec_b64 s[38:39], s[36:37]
	s_cbranch_execz .LBB0_465
	v_lshlrev_b32_e32 v0, 8, v5
	v_lshrrev_b32_e32 v7, 21, v4
	v_lshl_add_u32 v8, v5, 6, v172
	v_add3_u32 v9, v0, v162, v189
	s_mov_b64 s[42:43], 0
	v_readfirstlane_b32 s100, v186
	v_readfirstlane_b32 s101, v188
	ds_read2st64_b32 v[2:3], v9 offset1:1
	ds_read2st64_b32 v[0:1], v9 offset0:2 offset1:3
	s_add_i32 s99, s100, 0x3fc
	s_add_i32 s15, s101, 0x800
	s_mov_b32 s37, s101
	s_cmp_lg_u64 s[40:41], 0
	s_cselect_b32 s98, 4, -4
	s_cselect_b32 s36, s100, s99
	v_mov_b32_e32 v249, s98
.LBB0_444:
	v_add_u32_e32 v9, 0x400, v9
	v_add_u32_e32 v5, 4, v5
	ds_read2st64_b32 v[240:241], v9 offset1:1
	ds_read2st64_b32 v[242:243], v9 offset0:2 offset1:3
	v_cmp_ge_u32_e64 s[58:59], v5, v6
	s_waitcnt lgkmcnt(2)
	v_lshrrev_b32_e32 v244, 21, v2
	v_cmp_gt_u32_e64 s[44:45], v244, v7
	v_cmp_eq_u32_e64 s[46:47], v244, v7
	v_mov_b32_e32 v247, v8
	s_nop 0
	v_mbcnt_lo_u32_b32 v245, s44, 0
	v_mbcnt_hi_u32_b32 v245, s45, v245
	v_mbcnt_lo_u32_b32 v246, s46, 0
	v_mbcnt_hi_u32_b32 v246, s47, v246
	v_mad_i32_i24 v245, v245, v249, s36
	v_lshl_add_u32 v246, v246, 2, s37
	v_cmp_gt_i32_e64 s[48:49], s15, v246
	s_mov_b64 exec, s[44:45]
	ds_write_b32 v245, v247
	s_bcnt1_i32_b64 s44, s[44:45]
	s_and_b64 exec, s[46:47], s[48:49]
	ds_write_b32 v246, v247
	s_mov_b64 exec, -1
	s_bcnt1_i32_b64 s46, s[46:47]
	s_mul_i32 s44, s44, s98
	s_lshl2_add_u32 s37, s46, s37
	s_add_i32 s36, s36, s44
	v_lshrrev_b32_e32 v244, 21, v3
	v_cmp_gt_u32_e64 s[44:45], v244, v7
	v_cmp_eq_u32_e64 s[46:47], v244, v7
	v_add_u32_e32 v247, 0x40, v8
	s_nop 0
	v_mbcnt_lo_u32_b32 v245, s44, 0
	v_mbcnt_hi_u32_b32 v245, s45, v245
	v_mbcnt_lo_u32_b32 v246, s46, 0
	v_mbcnt_hi_u32_b32 v246, s47, v246
	v_mad_i32_i24 v245, v245, v249, s36
	v_lshl_add_u32 v246, v246, 2, s37
	v_cmp_gt_i32_e64 s[48:49], s15, v246
	s_mov_b64 exec, s[44:45]
	ds_write_b32 v245, v247
	s_bcnt1_i32_b64 s44, s[44:45]
	s_and_b64 exec, s[46:47], s[48:49]
	ds_write_b32 v246, v247
	s_mov_b64 exec, -1
	s_bcnt1_i32_b64 s46, s[46:47]
	s_mul_i32 s44, s44, s98
	s_lshl2_add_u32 s37, s46, s37
	s_add_i32 s36, s36, s44
	v_lshrrev_b32_e32 v244, 21, v0
	v_cmp_gt_u32_e64 s[44:45], v244, v7
	v_cmp_eq_u32_e64 s[46:47], v244, v7
	v_add_u32_e32 v247, 0x80, v8
	s_nop 0
	v_mbcnt_lo_u32_b32 v245, s44, 0
	v_mbcnt_hi_u32_b32 v245, s45, v245
	v_mbcnt_lo_u32_b32 v246, s46, 0
	v_mbcnt_hi_u32_b32 v246, s47, v246
	v_mad_i32_i24 v245, v245, v249, s36
	v_lshl_add_u32 v246, v246, 2, s37
	v_cmp_gt_i32_e64 s[48:49], s15, v246
	s_mov_b64 exec, s[44:45]
	ds_write_b32 v245, v247
	s_bcnt1_i32_b64 s44, s[44:45]
	s_and_b64 exec, s[46:47], s[48:49]
	ds_write_b32 v246, v247
	s_mov_b64 exec, -1
	s_bcnt1_i32_b64 s46, s[46:47]
	s_mul_i32 s44, s44, s98
	s_lshl2_add_u32 s37, s46, s37
	s_add_i32 s36, s36, s44
	v_lshrrev_b32_e32 v244, 21, v1
	v_cmp_gt_u32_e64 s[44:45], v244, v7
	v_cmp_eq_u32_e64 s[46:47], v244, v7
	v_add_u32_e32 v247, 0xc0, v8
	s_nop 0
	v_mbcnt_lo_u32_b32 v245, s44, 0
	v_mbcnt_hi_u32_b32 v245, s45, v245
	v_mbcnt_lo_u32_b32 v246, s46, 0
	v_mbcnt_hi_u32_b32 v246, s47, v246
	v_mad_i32_i24 v245, v245, v249, s36
	v_lshl_add_u32 v246, v246, 2, s37
	v_cmp_gt_i32_e64 s[48:49], s15, v246
	s_mov_b64 exec, s[44:45]
	ds_write_b32 v245, v247
	s_bcnt1_i32_b64 s44, s[44:45]
	s_and_b64 exec, s[46:47], s[48:49]
	ds_write_b32 v246, v247
	s_mov_b64 exec, -1
	s_bcnt1_i32_b64 s46, s[46:47]
	s_mul_i32 s44, s44, s98
	s_lshl2_add_u32 s37, s46, s37
	s_add_i32 s36, s36, s44
	v_add_u32_e32 v8, 0x100, v8
	s_waitcnt lgkmcnt(0)
	v_mov_b32_e32 v2, v240
	v_mov_b32_e32 v3, v241
	v_mov_b32_e32 v0, v242
	v_mov_b32_e32 v1, v243
	s_cmp_lg_u64 s[58:59], 0
	s_cbranch_scc0 .LBB0_444
	s_sub_i32 s37, s37, s101
	s_lshr_b32 s37, s37, 2
	s_sub_i32 s44, s36, s100
	s_sub_i32 s45, s99, s36
	s_cmp_lg_u64 s[40:41], 0
	s_cselect_b32 s36, s44, s45
	s_lshr_b32 s36, s36, 2
	v_mov_b32_e32 v2, s36
	v_mov_b32_e32 v3, s37
